# prompt attention unit rewritten by hand: K/V rows via LDS-DMA (global_load_lds, source-side XOR swizzle) instead of global_load+ds_write_b128; one shared routine for both query copies
# speedup vs baseline: 1.0402x; 1.0159x over previous
.LBB0_2557:
	s_lshl_b32 s41, s20, 10
	s_cmp_gt_u32 s40, 32
	s_cselect_b64 s[6:7], -1, 0
	s_cmp_gt_u32 s40, 64
	s_cselect_b64 s[8:9], -1, 0
	s_cmpk_gt_u32 s40, 0x60
	s_cselect_b64 s[26:27], -1, 0
	s_cmpk_gt_u32 s40, 0x80
	s_cselect_b64 s[28:29], -1, 0
	s_cmpk_gt_u32 s40, 0xa0
	s_cselect_b64 s[30:31], -1, 0
	s_cmpk_gt_u32 s40, 0xc0
	s_cselect_b64 s[34:35], -1, 0
	s_cmpk_gt_u32 s40, 0xe0
	s_cselect_b64 s[36:37], -1, 0
	s_lshl_b32 s0, s20, 11
	s_add_u32 s38, s56, s0
	s_addc_u32 s39, s57, 0
	s_mov_b32 s4, 0
	s_mov_b64 s[2:3], -1
	s_lshr_b32 s70, s41, 10
	s_mov_b32 s72, s48
	s_mov_b32 s73, s40
	s_mov_b32 s74, 0
	s_branch .Lau_entry
.Lau_entry:
	v_and_b32_e32 v3, 63, v0
	v_lshrrev_b32_e32 v4, 6, v0
	v_readfirstlane_b32 s75, v138
	v_and_b32_e32 v1, 15, v3
	v_readfirstlane_b32 s76, v4
	v_lshrrev_b32_e32 v2, 4, v3
	s_lshl_b32 s76, s76, 11
	s_add_i32 s76, s76, 0x24000
	v_lshl_add_u32 v4, v2, 2, v138
	ds_read2_b32 v[10:11], v4 offset0:0 offset1:4
	ds_read2_b32 v[12:13], v4 offset0:8 offset1:12
	ds_read2_b32 v[14:15], v4 offset0:16 offset1:20
	ds_read2_b32 v[16:17], v4 offset0:24 offset1:28
	ds_read2_b32 v[18:19], v4 offset0:32 offset1:36
	ds_read2_b32 v[20:21], v4 offset0:40 offset1:44
	ds_read2_b32 v[22:23], v4 offset0:48 offset1:52
	ds_read2_b32 v[24:25], v4 offset0:56 offset1:60
	ds_read2_b32 v[26:27], v4 offset0:64 offset1:68
	ds_read2_b32 v[28:29], v4 offset0:72 offset1:76
	ds_read2_b32 v[30:31], v4 offset0:80 offset1:84
	ds_read2_b32 v[32:33], v4 offset0:88 offset1:92
	ds_read2_b32 v[34:35], v4 offset0:96 offset1:100
	ds_read2_b32 v[36:37], v4 offset0:104 offset1:108
	ds_read2_b32 v[38:39], v4 offset0:112 offset1:116
	ds_read2_b32 v[40:41], v4 offset0:120 offset1:124
	ds_read2_b32 v[42:43], v4 offset0:128 offset1:132
	ds_read2_b32 v[44:45], v4 offset0:136 offset1:140
	ds_read2_b32 v[46:47], v4 offset0:144 offset1:148
	ds_read2_b32 v[48:49], v4 offset0:152 offset1:156
	ds_read2_b32 v[50:51], v4 offset0:160 offset1:164
	ds_read2_b32 v[52:53], v4 offset0:168 offset1:172
	ds_read2_b32 v[54:55], v4 offset0:176 offset1:180
	ds_read2_b32 v[56:57], v4 offset0:184 offset1:188
	ds_read2_b32 v[58:59], v4 offset0:192 offset1:196
	ds_read2_b32 v[60:61], v4 offset0:200 offset1:204
	ds_read2_b32 v[62:63], v4 offset0:208 offset1:212
	ds_read2_b32 v[64:65], v4 offset0:216 offset1:220
	ds_read2_b32 v[66:67], v4 offset0:224 offset1:228
	ds_read2_b32 v[68:69], v4 offset0:232 offset1:236
	ds_read2_b32 v[70:71], v4 offset0:240 offset1:244
	ds_read2_b32 v[72:73], v4 offset0:248 offset1:252
	v_readlane_b32 s40, v251, 27
	v_readlane_b32 s41, v251, 28
	v_readlane_b32 s42, v251, 29
	v_readlane_b32 s43, v251, 30
	v_readlane_b32 s44, v251, 31
	v_readlane_b32 s45, v251, 32
	v_readlane_b32 s46, v251, 49
	v_readlane_b32 s47, v251, 50
	s_lshl_b32 s8, s70, 11
	s_lshl_b32 s9, s72, 9
	s_add_u32 s56, s40, s8
	s_addc_u32 s57, s41, 0
	s_add_u32 s50, s42, s9
	s_addc_u32 s51, s43, 0
	s_add_u32 s52, s44, s9
	s_addc_u32 s53, s45, 0
	s_add_u32 s58, s46, s8
	s_addc_u32 s59, s47, 0
	v_lshlrev_b32_e32 v5, 1, v2
	v_xor_b32_e32 v5, v1, v5
	v_lshlrev_b32_e32 v5, 4, v5
	v_xor_b32_e32 v6, 0x80, v5
	v_and_b32_e32 v7, 3, v1
	v_and_b32_e32 v8, 8, v1
	v_lshl_or_b32 v8, v7, 1, v8
	v_or_b32_e32 v9, 0, v2
	v_xor_b32_e32 v9, v9, v8
	v_lshlrev_b32_e32 v9, 4, v9
	v_lshl_add_u32 v9, v1, 8, v9
	v_add_u32_e32 v74, s75, v9
	v_or_b32_e32 v9, 4, v2
	v_xor_b32_e32 v9, v9, v8
	v_lshlrev_b32_e32 v9, 4, v9
	v_lshl_add_u32 v9, v1, 8, v9
	v_add_u32_e32 v75, s75, v9
	v_or_b32_e32 v9, 8, v2
	v_xor_b32_e32 v9, v9, v8
	v_lshlrev_b32_e32 v9, 4, v9
	v_lshl_add_u32 v9, v1, 8, v9
	v_add_u32_e32 v76, s75, v9
	v_or_b32_e32 v9, 12, v2
	v_xor_b32_e32 v9, v9, v8
	v_lshlrev_b32_e32 v9, 4, v9
	v_lshl_add_u32 v9, v1, 8, v9
	v_add_u32_e32 v77, s75, v9
	v_lshrrev_b32_e32 v128, 2, v1
	v_lshl_or_b32 v129, v2, 3, v128
	v_and_b32_e32 v130, 1, v2
	v_lshl_or_b32 v130, v130, 2, v128
	v_lshlrev_b32_e32 v129, 8, v129
	v_lshl_add_u32 v129, v7, 3, v129
	v_add_u32_e32 v129, s75, v129
	v_xor_b32_e32 v9, 0, v130
	v_lshl_add_u32 v78, v9, 5, v129
	v_xor_b32_e32 v9, 1, v130
	v_lshl_add_u32 v79, v9, 5, v129
	v_xor_b32_e32 v9, 2, v130
	v_lshl_add_u32 v80, v9, 5, v129
	v_xor_b32_e32 v9, 3, v130
	v_lshl_add_u32 v81, v9, 5, v129
	v_xor_b32_e32 v9, 4, v130
	v_lshl_add_u32 v82, v9, 5, v129
	v_xor_b32_e32 v9, 5, v130
	v_lshl_add_u32 v83, v9, 5, v129
	v_xor_b32_e32 v9, 6, v130
	v_lshl_add_u32 v84, v9, 5, v129
	v_xor_b32_e32 v9, 7, v130
	v_lshl_add_u32 v85, v9, 5, v129
	v_lshl_add_u32 v86, v1, 4, s75
	v_lshl_add_u32 v87, v3, 4, s75
	v_lshl_add_u32 v88, v3, 1, s76
	v_cmp_gt_u32_e64 s[20:21], 4, v1
	v_lshlrev_b32_e32 v9, 4, v2
	v_lshl_add_u32 v128, v7, 9, v9
	v_add_u32_e32 v128, s76, v128
	v_add_u32_e32 v131, 0x22000, v9
	v_cndmask_b32_e64 v89, v131, v128, s[20:21]
	v_lshlrev_b32_e32 v90, 1, v1
	v_lshl_add_u32 v91, v7, 8, v9
	v_mov_b32_e32 v128, 0
	v_mov_b32_e32 v129, 0
	v_lshlrev_b32_e32 v9, 3, v3
	v_add_u32_e32 v9, 0x22000, v9
	ds_write_b64 v9, v[128:129]
	v_cmp_gt_u32_e64 s[24:25], s73, v3
	v_add_u32_e32 v9, 64, v3
	v_cmp_gt_u32_e64 s[26:27], s73, v9
	v_add_u32_e32 v9, 0x80, v3
	v_cmp_gt_u32_e64 s[28:29], s73, v9
	v_add_u32_e32 v9, 0xc0, v3
	v_cmp_gt_u32_e64 s[30:31], s73, v9
	s_waitcnt lgkmcnt(0)
	v_lshl_add_u32 v10, v10, 9, v5
	v_lshl_add_u32 v11, v11, 9, v5
	v_lshl_add_u32 v12, v12, 9, v6
	v_lshl_add_u32 v13, v13, 9, v6
	v_lshl_add_u32 v14, v14, 9, v5
	v_lshl_add_u32 v15, v15, 9, v5
	v_lshl_add_u32 v16, v16, 9, v6
	v_lshl_add_u32 v17, v17, 9, v6
	v_lshl_add_u32 v18, v18, 9, v5
	v_lshl_add_u32 v19, v19, 9, v5
	v_lshl_add_u32 v20, v20, 9, v6
	v_lshl_add_u32 v21, v21, 9, v6
	v_lshl_add_u32 v22, v22, 9, v5
	v_lshl_add_u32 v23, v23, 9, v5
	v_lshl_add_u32 v24, v24, 9, v6
	v_lshl_add_u32 v25, v25, 9, v6
	v_lshl_add_u32 v26, v26, 9, v5
	v_lshl_add_u32 v27, v27, 9, v5
	v_lshl_add_u32 v28, v28, 9, v6
	v_lshl_add_u32 v29, v29, 9, v6
	v_lshl_add_u32 v30, v30, 9, v5
	v_lshl_add_u32 v31, v31, 9, v5
	v_lshl_add_u32 v32, v32, 9, v6
	v_lshl_add_u32 v33, v33, 9, v6
	v_lshl_add_u32 v34, v34, 9, v5
	v_lshl_add_u32 v35, v35, 9, v5
	v_lshl_add_u32 v36, v36, 9, v6
	v_lshl_add_u32 v37, v37, 9, v6
	v_lshl_add_u32 v38, v38, 9, v5
	v_lshl_add_u32 v39, v39, 9, v5
	v_lshl_add_u32 v40, v40, 9, v6
	v_lshl_add_u32 v41, v41, 9, v6
	v_lshl_add_u32 v42, v42, 9, v5
	v_lshl_add_u32 v43, v43, 9, v5
	v_lshl_add_u32 v44, v44, 9, v6
	v_lshl_add_u32 v45, v45, 9, v6
	v_lshl_add_u32 v46, v46, 9, v5
	v_lshl_add_u32 v47, v47, 9, v5
	v_lshl_add_u32 v48, v48, 9, v6
	v_lshl_add_u32 v49, v49, 9, v6
	v_lshl_add_u32 v50, v50, 9, v5
	v_lshl_add_u32 v51, v51, 9, v5
	v_lshl_add_u32 v52, v52, 9, v6
	v_lshl_add_u32 v53, v53, 9, v6
	v_lshl_add_u32 v54, v54, 9, v5
	v_lshl_add_u32 v55, v55, 9, v5
	v_lshl_add_u32 v56, v56, 9, v6
	v_lshl_add_u32 v57, v57, 9, v6
	v_lshl_add_u32 v58, v58, 9, v5
	v_lshl_add_u32 v59, v59, 9, v5
	v_lshl_add_u32 v60, v60, 9, v6
	v_lshl_add_u32 v61, v61, 9, v6
	v_lshl_add_u32 v62, v62, 9, v5
	v_lshl_add_u32 v63, v63, 9, v5
	v_lshl_add_u32 v64, v64, 9, v6
	v_lshl_add_u32 v65, v65, 9, v6
	v_lshl_add_u32 v66, v66, 9, v5
	v_lshl_add_u32 v67, v67, 9, v5
	v_lshl_add_u32 v68, v68, 9, v6
	v_lshl_add_u32 v69, v69, 9, v6
	v_lshl_add_u32 v70, v70, 9, v5
	v_lshl_add_u32 v71, v71, 9, v5
	v_lshl_add_u32 v72, v72, 9, v6
	v_lshl_add_u32 v73, v73, 9, v6
	s_mov_b32 s71, 0
.Lau_g:
	s_lshl_b32 s8, s71, 8
	s_lshl_b32 s9, s71, 10
	s_add_u32 s0, s50, s8
	s_addc_u32 s1, s51, 0
	s_add_u32 s2, s52, s8
	s_addc_u32 s3, s53, 0
	s_add_u32 s4, s56, s9
	s_addc_u32 s5, s57, 0
	s_add_u32 s6, s58, s9
	s_addc_u32 s7, s59, 0
	global_load_dwordx4 v[92:95], v91, s[4:5] offset:0
	global_load_dwordx4 v[96:99], v91, s[4:5] offset:64
	global_load_dwordx4 v[100:103], v91, s[4:5] offset:128
	global_load_dwordx4 v[104:107], v91, s[4:5] offset:192
	s_add_i32 m0, s75, 0x1400
	s_nop 0
	global_load_lds_dwordx4 v10, s[0:1]
	s_add_i32 m0, s75, 0x1800
	s_nop 0
	global_load_lds_dwordx4 v11, s[0:1]
	s_add_i32 m0, s75, 0x1c00
	s_nop 0
	global_load_lds_dwordx4 v12, s[0:1]
	s_add_i32 m0, s75, 0x2000
	s_nop 0
	global_load_lds_dwordx4 v13, s[0:1]
	s_add_i32 m0, s75, 0x2400
	s_nop 0
	global_load_lds_dwordx4 v14, s[0:1]
	s_add_i32 m0, s75, 0x2800
	s_nop 0
	global_load_lds_dwordx4 v15, s[0:1]
	s_add_i32 m0, s75, 0x2c00
	s_nop 0
	global_load_lds_dwordx4 v16, s[0:1]
	s_add_i32 m0, s75, 0x3000
	s_nop 0
	global_load_lds_dwordx4 v17, s[0:1]
	s_add_i32 m0, s75, 0x3400
	s_nop 0
	global_load_lds_dwordx4 v18, s[0:1]
	s_add_i32 m0, s75, 0x3800
	s_nop 0
	global_load_lds_dwordx4 v19, s[0:1]
	s_add_i32 m0, s75, 0x3c00
	s_nop 0
	global_load_lds_dwordx4 v20, s[0:1]
	s_add_i32 m0, s75, 0x4000
	s_nop 0
	global_load_lds_dwordx4 v21, s[0:1]
	s_waitcnt vmcnt(8)
	ds_read_b128 v[108:111], v74 offset:5120
	ds_read_b128 v[112:115], v75 offset:5120
	ds_read_b128 v[116:119], v76 offset:5120
	ds_read_b128 v[120:123], v77 offset:5120
	v_cndmask_b32_e64 v92, 0, v92, s[20:21]
	v_cndmask_b32_e64 v93, 0, v93, s[20:21]
	v_cndmask_b32_e64 v94, 0, v94, s[20:21]
	v_cndmask_b32_e64 v95, 0, v95, s[20:21]
	v_cndmask_b32_e64 v96, 0, v96, s[20:21]
	v_cndmask_b32_e64 v97, 0, v97, s[20:21]
	v_cndmask_b32_e64 v98, 0, v98, s[20:21]
	v_cndmask_b32_e64 v99, 0, v99, s[20:21]
	v_cndmask_b32_e64 v100, 0, v100, s[20:21]
	v_cndmask_b32_e64 v101, 0, v101, s[20:21]
	v_cndmask_b32_e64 v102, 0, v102, s[20:21]
	v_cndmask_b32_e64 v103, 0, v103, s[20:21]
	v_cndmask_b32_e64 v104, 0, v104, s[20:21]
	v_cndmask_b32_e64 v105, 0, v105, s[20:21]
	v_cndmask_b32_e64 v106, 0, v106, s[20:21]
	v_cndmask_b32_e64 v107, 0, v107, s[20:21]
	s_waitcnt lgkmcnt(0)
	v_mfma_f32_16x16x32_bf16 v[124:127], v[92:95], v[108:111], 0
	v_mfma_f32_16x16x32_bf16 v[124:127], v[96:99], v[112:115], v[124:127]
	v_mfma_f32_16x16x32_bf16 v[124:127], v[100:103], v[116:119], v[124:127]
	v_mfma_f32_16x16x32_bf16 v[124:127], v[104:107], v[120:123], v[124:127]
	s_add_i32 m0, s75, 0x1400
	s_nop 0
	global_load_lds_dwordx4 v22, s[0:1]
	s_add_i32 m0, s75, 0x1800
	s_nop 0
	global_load_lds_dwordx4 v23, s[0:1]
	s_add_i32 m0, s75, 0x1c00
	s_nop 0
	global_load_lds_dwordx4 v24, s[0:1]
	s_add_i32 m0, s75, 0x2000
	s_nop 0
	global_load_lds_dwordx4 v25, s[0:1]
	s_mov_b64 exec, 0xffff
	ds_write_b128 v86, v[124:127] offset:1024
	s_mov_b64 exec, -1
	s_waitcnt vmcnt(8)
	ds_read_b128 v[108:111], v74 offset:9216
	ds_read_b128 v[112:115], v75 offset:9216
	ds_read_b128 v[116:119], v76 offset:9216
	ds_read_b128 v[120:123], v77 offset:9216
	s_waitcnt lgkmcnt(0)
	v_mfma_f32_16x16x32_bf16 v[124:127], v[92:95], v[108:111], 0
	v_mfma_f32_16x16x32_bf16 v[124:127], v[96:99], v[112:115], v[124:127]
	v_mfma_f32_16x16x32_bf16 v[124:127], v[100:103], v[116:119], v[124:127]
	v_mfma_f32_16x16x32_bf16 v[124:127], v[104:107], v[120:123], v[124:127]
	s_add_i32 m0, s75, 0x2400
	s_nop 0
	global_load_lds_dwordx4 v26, s[0:1]
	s_add_i32 m0, s75, 0x2800
	s_nop 0
	global_load_lds_dwordx4 v27, s[0:1]
	s_add_i32 m0, s75, 0x2c00
	s_nop 0
	global_load_lds_dwordx4 v28, s[0:1]
	s_add_i32 m0, s75, 0x3000
	s_nop 0
	global_load_lds_dwordx4 v29, s[0:1]
	s_mov_b64 exec, 0xffff
	ds_write_b128 v86, v[124:127] offset:1280
	s_mov_b64 exec, -1
	s_waitcnt vmcnt(8)
	ds_read_b128 v[108:111], v74 offset:13312
	ds_read_b128 v[112:115], v75 offset:13312
	ds_read_b128 v[116:119], v76 offset:13312
	ds_read_b128 v[120:123], v77 offset:13312
	s_waitcnt lgkmcnt(0)
	v_mfma_f32_16x16x32_bf16 v[124:127], v[92:95], v[108:111], 0
	v_mfma_f32_16x16x32_bf16 v[124:127], v[96:99], v[112:115], v[124:127]
	v_mfma_f32_16x16x32_bf16 v[124:127], v[100:103], v[116:119], v[124:127]
	v_mfma_f32_16x16x32_bf16 v[124:127], v[104:107], v[120:123], v[124:127]
	s_add_i32 m0, s75, 0x3400
	s_nop 0
	global_load_lds_dwordx4 v30, s[0:1]
	s_add_i32 m0, s75, 0x3800
	s_nop 0
	global_load_lds_dwordx4 v31, s[0:1]
	s_add_i32 m0, s75, 0x3c00
	s_nop 0
	global_load_lds_dwordx4 v32, s[0:1]
	s_add_i32 m0, s75, 0x4000
	s_nop 0
	global_load_lds_dwordx4 v33, s[0:1]
	s_mov_b64 exec, 0xffff
	ds_write_b128 v86, v[124:127] offset:1536
	s_mov_b64 exec, -1
	s_waitcnt vmcnt(8)
	ds_read_b128 v[108:111], v74 offset:5120
	ds_read_b128 v[112:115], v75 offset:5120
	ds_read_b128 v[116:119], v76 offset:5120
	ds_read_b128 v[120:123], v77 offset:5120
	s_waitcnt lgkmcnt(0)
	v_mfma_f32_16x16x32_bf16 v[124:127], v[92:95], v[108:111], 0
	v_mfma_f32_16x16x32_bf16 v[124:127], v[96:99], v[112:115], v[124:127]
	v_mfma_f32_16x16x32_bf16 v[124:127], v[100:103], v[116:119], v[124:127]
	v_mfma_f32_16x16x32_bf16 v[124:127], v[104:107], v[120:123], v[124:127]
	s_add_i32 m0, s75, 0x1400
	s_nop 0
	global_load_lds_dwordx4 v34, s[0:1]
	s_add_i32 m0, s75, 0x1800
	s_nop 0
	global_load_lds_dwordx4 v35, s[0:1]
	s_add_i32 m0, s75, 0x1c00
	s_nop 0
	global_load_lds_dwordx4 v36, s[0:1]
	s_add_i32 m0, s75, 0x2000
	s_nop 0
	global_load_lds_dwordx4 v37, s[0:1]
	s_mov_b64 exec, 0xffff
	ds_write_b128 v86, v[124:127] offset:1792
	s_mov_b64 exec, -1
	s_waitcnt vmcnt(8)
	ds_read_b128 v[108:111], v74 offset:9216
	ds_read_b128 v[112:115], v75 offset:9216
	ds_read_b128 v[116:119], v76 offset:9216
	ds_read_b128 v[120:123], v77 offset:9216
	s_waitcnt lgkmcnt(0)
	v_mfma_f32_16x16x32_bf16 v[124:127], v[92:95], v[108:111], 0
	v_mfma_f32_16x16x32_bf16 v[124:127], v[96:99], v[112:115], v[124:127]
	v_mfma_f32_16x16x32_bf16 v[124:127], v[100:103], v[116:119], v[124:127]
	v_mfma_f32_16x16x32_bf16 v[124:127], v[104:107], v[120:123], v[124:127]
	s_add_i32 m0, s75, 0x2400
	s_nop 0
	global_load_lds_dwordx4 v38, s[0:1]
	s_add_i32 m0, s75, 0x2800
	s_nop 0
	global_load_lds_dwordx4 v39, s[0:1]
	s_add_i32 m0, s75, 0x2c00
	s_nop 0
	global_load_lds_dwordx4 v40, s[0:1]
	s_add_i32 m0, s75, 0x3000
	s_nop 0
	global_load_lds_dwordx4 v41, s[0:1]
	s_mov_b64 exec, 0xffff
	ds_write_b128 v86, v[124:127] offset:2048
	s_mov_b64 exec, -1
	s_waitcnt vmcnt(8)
	ds_read_b128 v[108:111], v74 offset:13312
	ds_read_b128 v[112:115], v75 offset:13312
	ds_read_b128 v[116:119], v76 offset:13312
	ds_read_b128 v[120:123], v77 offset:13312
	s_waitcnt lgkmcnt(0)
	v_mfma_f32_16x16x32_bf16 v[124:127], v[92:95], v[108:111], 0
	v_mfma_f32_16x16x32_bf16 v[124:127], v[96:99], v[112:115], v[124:127]
	v_mfma_f32_16x16x32_bf16 v[124:127], v[100:103], v[116:119], v[124:127]
	v_mfma_f32_16x16x32_bf16 v[124:127], v[104:107], v[120:123], v[124:127]
	s_add_i32 m0, s75, 0x3400
	s_nop 0
	global_load_lds_dwordx4 v42, s[0:1]
	s_add_i32 m0, s75, 0x3800
	s_nop 0
	global_load_lds_dwordx4 v43, s[0:1]
	s_add_i32 m0, s75, 0x3c00
	s_nop 0
	global_load_lds_dwordx4 v44, s[0:1]
	s_add_i32 m0, s75, 0x4000
	s_nop 0
	global_load_lds_dwordx4 v45, s[0:1]
	s_mov_b64 exec, 0xffff
	ds_write_b128 v86, v[124:127] offset:2304
	s_mov_b64 exec, -1
	s_waitcnt vmcnt(8)
	ds_read_b128 v[108:111], v74 offset:5120
	ds_read_b128 v[112:115], v75 offset:5120
	ds_read_b128 v[116:119], v76 offset:5120
	ds_read_b128 v[120:123], v77 offset:5120
	s_waitcnt lgkmcnt(0)
	v_mfma_f32_16x16x32_bf16 v[124:127], v[92:95], v[108:111], 0
	v_mfma_f32_16x16x32_bf16 v[124:127], v[96:99], v[112:115], v[124:127]
	v_mfma_f32_16x16x32_bf16 v[124:127], v[100:103], v[116:119], v[124:127]
	v_mfma_f32_16x16x32_bf16 v[124:127], v[104:107], v[120:123], v[124:127]
	s_add_i32 m0, s75, 0x1400
	s_nop 0
	global_load_lds_dwordx4 v46, s[0:1]
	s_add_i32 m0, s75, 0x1800
	s_nop 0
	global_load_lds_dwordx4 v47, s[0:1]
	s_add_i32 m0, s75, 0x1c00
	s_nop 0
	global_load_lds_dwordx4 v48, s[0:1]
	s_add_i32 m0, s75, 0x2000
	s_nop 0
	global_load_lds_dwordx4 v49, s[0:1]
	s_mov_b64 exec, 0xffff
	ds_write_b128 v86, v[124:127] offset:2560
	s_mov_b64 exec, -1
	s_waitcnt vmcnt(8)
	ds_read_b128 v[108:111], v74 offset:9216
	ds_read_b128 v[112:115], v75 offset:9216
	ds_read_b128 v[116:119], v76 offset:9216
	ds_read_b128 v[120:123], v77 offset:9216
	s_waitcnt lgkmcnt(0)
	v_mfma_f32_16x16x32_bf16 v[124:127], v[92:95], v[108:111], 0
	v_mfma_f32_16x16x32_bf16 v[124:127], v[96:99], v[112:115], v[124:127]
	v_mfma_f32_16x16x32_bf16 v[124:127], v[100:103], v[116:119], v[124:127]
	v_mfma_f32_16x16x32_bf16 v[124:127], v[104:107], v[120:123], v[124:127]
	s_add_i32 m0, s75, 0x2400
	s_nop 0
	global_load_lds_dwordx4 v50, s[0:1]
	s_add_i32 m0, s75, 0x2800
	s_nop 0
	global_load_lds_dwordx4 v51, s[0:1]
	s_add_i32 m0, s75, 0x2c00
	s_nop 0
	global_load_lds_dwordx4 v52, s[0:1]
	s_add_i32 m0, s75, 0x3000
	s_nop 0
	global_load_lds_dwordx4 v53, s[0:1]
	s_mov_b64 exec, 0xffff
	ds_write_b128 v86, v[124:127] offset:2816
	s_mov_b64 exec, -1
	s_waitcnt vmcnt(8)
	ds_read_b128 v[108:111], v74 offset:13312
	ds_read_b128 v[112:115], v75 offset:13312
	ds_read_b128 v[116:119], v76 offset:13312
	ds_read_b128 v[120:123], v77 offset:13312
	s_waitcnt lgkmcnt(0)
	v_mfma_f32_16x16x32_bf16 v[124:127], v[92:95], v[108:111], 0
	v_mfma_f32_16x16x32_bf16 v[124:127], v[96:99], v[112:115], v[124:127]
	v_mfma_f32_16x16x32_bf16 v[124:127], v[100:103], v[116:119], v[124:127]
	v_mfma_f32_16x16x32_bf16 v[124:127], v[104:107], v[120:123], v[124:127]
	s_add_i32 m0, s75, 0x3400
	s_nop 0
	global_load_lds_dwordx4 v54, s[0:1]
	s_add_i32 m0, s75, 0x3800
	s_nop 0
	global_load_lds_dwordx4 v55, s[0:1]
	s_add_i32 m0, s75, 0x3c00
	s_nop 0
	global_load_lds_dwordx4 v56, s[0:1]
	s_add_i32 m0, s75, 0x4000
	s_nop 0
	global_load_lds_dwordx4 v57, s[0:1]
	s_mov_b64 exec, 0xffff
	ds_write_b128 v86, v[124:127] offset:3072
	s_mov_b64 exec, -1
	s_waitcnt vmcnt(8)
	ds_read_b128 v[108:111], v74 offset:5120
	ds_read_b128 v[112:115], v75 offset:5120
	ds_read_b128 v[116:119], v76 offset:5120
	ds_read_b128 v[120:123], v77 offset:5120
	s_waitcnt lgkmcnt(0)
	v_mfma_f32_16x16x32_bf16 v[124:127], v[92:95], v[108:111], 0
	v_mfma_f32_16x16x32_bf16 v[124:127], v[96:99], v[112:115], v[124:127]
	v_mfma_f32_16x16x32_bf16 v[124:127], v[100:103], v[116:119], v[124:127]
	v_mfma_f32_16x16x32_bf16 v[124:127], v[104:107], v[120:123], v[124:127]
	s_add_i32 m0, s75, 0x1400
	s_nop 0
	global_load_lds_dwordx4 v58, s[0:1]
	s_add_i32 m0, s75, 0x1800
	s_nop 0
	global_load_lds_dwordx4 v59, s[0:1]
	s_add_i32 m0, s75, 0x1c00
	s_nop 0
	global_load_lds_dwordx4 v60, s[0:1]
	s_add_i32 m0, s75, 0x2000
	s_nop 0
	global_load_lds_dwordx4 v61, s[0:1]
	s_mov_b64 exec, 0xffff
	ds_write_b128 v86, v[124:127] offset:3328
	s_mov_b64 exec, -1
	s_waitcnt vmcnt(8)
	ds_read_b128 v[108:111], v74 offset:9216
	ds_read_b128 v[112:115], v75 offset:9216
	ds_read_b128 v[116:119], v76 offset:9216
	ds_read_b128 v[120:123], v77 offset:9216
	s_waitcnt lgkmcnt(0)
	v_mfma_f32_16x16x32_bf16 v[124:127], v[92:95], v[108:111], 0
	v_mfma_f32_16x16x32_bf16 v[124:127], v[96:99], v[112:115], v[124:127]
	v_mfma_f32_16x16x32_bf16 v[124:127], v[100:103], v[116:119], v[124:127]
	v_mfma_f32_16x16x32_bf16 v[124:127], v[104:107], v[120:123], v[124:127]
	s_add_i32 m0, s75, 0x2400
	s_nop 0
	global_load_lds_dwordx4 v62, s[0:1]
	s_add_i32 m0, s75, 0x2800
	s_nop 0
	global_load_lds_dwordx4 v63, s[0:1]
	s_add_i32 m0, s75, 0x2c00
	s_nop 0
	global_load_lds_dwordx4 v64, s[0:1]
	s_add_i32 m0, s75, 0x3000
	s_nop 0
	global_load_lds_dwordx4 v65, s[0:1]
	s_mov_b64 exec, 0xffff
	ds_write_b128 v86, v[124:127] offset:3584
	s_mov_b64 exec, -1
	s_waitcnt vmcnt(8)
	ds_read_b128 v[108:111], v74 offset:13312
	ds_read_b128 v[112:115], v75 offset:13312
	ds_read_b128 v[116:119], v76 offset:13312
	ds_read_b128 v[120:123], v77 offset:13312
	s_waitcnt lgkmcnt(0)
	v_mfma_f32_16x16x32_bf16 v[124:127], v[92:95], v[108:111], 0
	v_mfma_f32_16x16x32_bf16 v[124:127], v[96:99], v[112:115], v[124:127]
	v_mfma_f32_16x16x32_bf16 v[124:127], v[100:103], v[116:119], v[124:127]
	v_mfma_f32_16x16x32_bf16 v[124:127], v[104:107], v[120:123], v[124:127]
	s_add_i32 m0, s75, 0x3400
	s_nop 0
	global_load_lds_dwordx4 v66, s[0:1]
	s_add_i32 m0, s75, 0x3800
	s_nop 0
	global_load_lds_dwordx4 v67, s[0:1]
	s_add_i32 m0, s75, 0x3c00
	s_nop 0
	global_load_lds_dwordx4 v68, s[0:1]
	s_add_i32 m0, s75, 0x4000
	s_nop 0
	global_load_lds_dwordx4 v69, s[0:1]
	s_mov_b64 exec, 0xffff
	ds_write_b128 v86, v[124:127] offset:3840
	s_mov_b64 exec, -1
	s_waitcnt vmcnt(8)
	ds_read_b128 v[108:111], v74 offset:5120
	ds_read_b128 v[112:115], v75 offset:5120
	ds_read_b128 v[116:119], v76 offset:5120
	ds_read_b128 v[120:123], v77 offset:5120
	s_waitcnt lgkmcnt(0)
	v_mfma_f32_16x16x32_bf16 v[124:127], v[92:95], v[108:111], 0
	v_mfma_f32_16x16x32_bf16 v[124:127], v[96:99], v[112:115], v[124:127]
	v_mfma_f32_16x16x32_bf16 v[124:127], v[100:103], v[116:119], v[124:127]
	v_mfma_f32_16x16x32_bf16 v[124:127], v[104:107], v[120:123], v[124:127]
	s_add_i32 m0, s75, 0x1400
	s_nop 0
	global_load_lds_dwordx4 v70, s[0:1]
	s_add_i32 m0, s75, 0x1800
	s_nop 0
	global_load_lds_dwordx4 v71, s[0:1]
	s_add_i32 m0, s75, 0x1c00
	s_nop 0
	global_load_lds_dwordx4 v72, s[0:1]
	s_add_i32 m0, s75, 0x2000
	s_nop 0
	global_load_lds_dwordx4 v73, s[0:1]
	s_mov_b64 exec, 0xffff
	ds_write_b128 v86, v[124:127] offset:4096
	s_mov_b64 exec, -1
	s_waitcnt vmcnt(8)
	ds_read_b128 v[108:111], v74 offset:9216
	ds_read_b128 v[112:115], v75 offset:9216
	ds_read_b128 v[116:119], v76 offset:9216
	ds_read_b128 v[120:123], v77 offset:9216
	s_waitcnt lgkmcnt(0)
	v_mfma_f32_16x16x32_bf16 v[124:127], v[92:95], v[108:111], 0
	v_mfma_f32_16x16x32_bf16 v[124:127], v[96:99], v[112:115], v[124:127]
	v_mfma_f32_16x16x32_bf16 v[124:127], v[100:103], v[116:119], v[124:127]
	v_mfma_f32_16x16x32_bf16 v[124:127], v[104:107], v[120:123], v[124:127]
	s_nop 7
	s_nop 1
	s_mov_b64 exec, 0xffff
	ds_write_b128 v86, v[124:127] offset:4352
	s_mov_b64 exec, -1
	s_waitcnt vmcnt(4)
	ds_read_b128 v[108:111], v74 offset:13312
	ds_read_b128 v[112:115], v75 offset:13312
	ds_read_b128 v[116:119], v76 offset:13312
	ds_read_b128 v[120:123], v77 offset:13312
	s_waitcnt lgkmcnt(0)
	v_mfma_f32_16x16x32_bf16 v[124:127], v[92:95], v[108:111], 0
	v_mfma_f32_16x16x32_bf16 v[124:127], v[96:99], v[112:115], v[124:127]
	v_mfma_f32_16x16x32_bf16 v[124:127], v[100:103], v[116:119], v[124:127]
	v_mfma_f32_16x16x32_bf16 v[124:127], v[104:107], v[120:123], v[124:127]
	s_nop 7
	s_nop 1
	s_mov_b64 exec, 0xffff
	ds_write_b128 v86, v[124:127] offset:4608
	s_mov_b64 exec, -1
	s_waitcnt vmcnt(0)
	ds_read_b128 v[108:111], v74 offset:5120
	ds_read_b128 v[112:115], v75 offset:5120
	ds_read_b128 v[116:119], v76 offset:5120
	ds_read_b128 v[120:123], v77 offset:5120
	s_waitcnt lgkmcnt(0)
	v_mfma_f32_16x16x32_bf16 v[124:127], v[92:95], v[108:111], 0
	v_mfma_f32_16x16x32_bf16 v[124:127], v[96:99], v[112:115], v[124:127]
	v_mfma_f32_16x16x32_bf16 v[124:127], v[100:103], v[116:119], v[124:127]
	v_mfma_f32_16x16x32_bf16 v[124:127], v[104:107], v[120:123], v[124:127]
	s_nop 7
	s_nop 1
	s_mov_b64 exec, 0xffff
	ds_write_b128 v86, v[124:127] offset:4864
	s_mov_b64 exec, -1
	s_add_i32 m0, s75, 0x2400
	s_nop 0
	global_load_lds_dwordx4 v10, s[2:3]
	s_add_i32 m0, s75, 0x2800
	s_nop 0
	global_load_lds_dwordx4 v11, s[2:3]
	s_add_i32 m0, s75, 0x2c00
	s_nop 0
	global_load_lds_dwordx4 v12, s[2:3]
	s_add_i32 m0, s75, 0x3000
	s_nop 0
	global_load_lds_dwordx4 v13, s[2:3]
	s_add_i32 m0, s75, 0x3400
	s_nop 0
	global_load_lds_dwordx4 v14, s[2:3]
	s_add_i32 m0, s75, 0x3800
	s_nop 0
	global_load_lds_dwordx4 v15, s[2:3]
	s_add_i32 m0, s75, 0x3c00
	s_nop 0
	global_load_lds_dwordx4 v16, s[2:3]
	s_add_i32 m0, s75, 0x4000
	s_nop 0
	global_load_lds_dwordx4 v17, s[2:3]
	s_waitcnt lgkmcnt(0)
	ds_read_b128 v[108:111], v87 offset:1024
	ds_read_b128 v[112:115], v87 offset:2048
	ds_read_b128 v[116:119], v87 offset:3072
	ds_read_b128 v[120:123], v87 offset:4096
	s_waitcnt lgkmcnt(0)
	s_add_i32 m0, s75, 0x400
	s_nop 0
	global_load_lds_dwordx4 v18, s[2:3]
	s_add_i32 m0, s75, 0x800
	s_nop 0
	global_load_lds_dwordx4 v19, s[2:3]
	s_add_i32 m0, s75, 0xc00
	s_nop 0
	global_load_lds_dwordx4 v20, s[2:3]
	s_add_i32 m0, s75, 0x1000
	s_nop 0
	global_load_lds_dwordx4 v21, s[2:3]
	s_add_i32 m0, s75, 0x1400
	s_nop 0
	global_load_lds_dwordx4 v22, s[2:3]
	s_add_i32 m0, s75, 0x1800
	s_nop 0
	global_load_lds_dwordx4 v23, s[2:3]
	s_add_i32 m0, s75, 0x1c00
	s_nop 0
	global_load_lds_dwordx4 v24, s[2:3]
	s_add_i32 m0, s75, 0x2000
	s_nop 0
	global_load_lds_dwordx4 v25, s[2:3]
	s_cmp_eq_u32 s73, 0x100
	s_cbranch_scc1 .Lau_nomask1
	v_mov_b32_e32 v9, 0xff61b1e6
	v_cndmask_b32_e64 v108, v9, v108, s[24:25]
	v_cndmask_b32_e64 v109, v9, v109, s[24:25]
	v_cndmask_b32_e64 v110, v9, v110, s[24:25]
	v_cndmask_b32_e64 v111, v9, v111, s[24:25]
	v_cndmask_b32_e64 v112, v9, v112, s[26:27]
	v_cndmask_b32_e64 v113, v9, v113, s[26:27]
	v_cndmask_b32_e64 v114, v9, v114, s[26:27]
	v_cndmask_b32_e64 v115, v9, v115, s[26:27]
	v_cndmask_b32_e64 v116, v9, v116, s[28:29]
	v_cndmask_b32_e64 v117, v9, v117, s[28:29]
	v_cndmask_b32_e64 v118, v9, v118, s[28:29]
	v_cndmask_b32_e64 v119, v9, v119, s[28:29]
	v_cndmask_b32_e64 v120, v9, v120, s[30:31]
	v_cndmask_b32_e64 v121, v9, v121, s[30:31]
	v_cndmask_b32_e64 v122, v9, v122, s[30:31]
	v_cndmask_b32_e64 v123, v9, v123, s[30:31]
.Lau_nomask1:
	v_max_f32_e32 v216, v108, v112
	v_max_f32_e32 v217, v109, v113
	v_max_f32_e32 v218, v110, v114
	v_max_f32_e32 v219, v111, v115
	v_max3_f32 v216, v116, v120, v216
	v_max3_f32 v217, v117, v121, v217
	v_max3_f32 v218, v118, v122, v218
	v_max3_f32 v219, v119, v123, v219
	v_max_f32_dpp v216, v216, v216 quad_perm:[1,0,3,2] row_mask:0xf bank_mask:0xf bound_ctrl:1
	v_max_f32_dpp v217, v217, v217 quad_perm:[1,0,3,2] row_mask:0xf bank_mask:0xf bound_ctrl:1
	v_max_f32_dpp v218, v218, v218 quad_perm:[1,0,3,2] row_mask:0xf bank_mask:0xf bound_ctrl:1
	v_max_f32_dpp v219, v219, v219 quad_perm:[1,0,3,2] row_mask:0xf bank_mask:0xf bound_ctrl:1
	v_max_f32_dpp v216, v216, v216 quad_perm:[2,3,0,1] row_mask:0xf bank_mask:0xf bound_ctrl:1
	v_max_f32_dpp v217, v217, v217 quad_perm:[2,3,0,1] row_mask:0xf bank_mask:0xf bound_ctrl:1
	v_max_f32_dpp v218, v218, v218 quad_perm:[2,3,0,1] row_mask:0xf bank_mask:0xf bound_ctrl:1
	v_max_f32_dpp v219, v219, v219 quad_perm:[2,3,0,1] row_mask:0xf bank_mask:0xf bound_ctrl:1
	v_max_f32_dpp v216, v216, v216 row_half_mirror row_mask:0xf bank_mask:0xf bound_ctrl:1
	v_max_f32_dpp v217, v217, v217 row_half_mirror row_mask:0xf bank_mask:0xf bound_ctrl:1
	v_max_f32_dpp v218, v218, v218 row_half_mirror row_mask:0xf bank_mask:0xf bound_ctrl:1
	v_max_f32_dpp v219, v219, v219 row_half_mirror row_mask:0xf bank_mask:0xf bound_ctrl:1
	v_max_f32_dpp v216, v216, v216 row_mirror row_mask:0xf bank_mask:0xf bound_ctrl:1
	v_max_f32_dpp v217, v217, v217 row_mirror row_mask:0xf bank_mask:0xf bound_ctrl:1
	v_max_f32_dpp v218, v218, v218 row_mirror row_mask:0xf bank_mask:0xf bound_ctrl:1
	v_max_f32_dpp v219, v219, v219 row_mirror row_mask:0xf bank_mask:0xf bound_ctrl:1
	v_max_f32_dpp v216, v216, v216 row_bcast:15 row_mask:0xa bank_mask:0xf
	v_max_f32_dpp v217, v217, v217 row_bcast:15 row_mask:0xa bank_mask:0xf
	v_max_f32_dpp v218, v218, v218 row_bcast:15 row_mask:0xa bank_mask:0xf
	v_max_f32_dpp v219, v219, v219 row_bcast:15 row_mask:0xa bank_mask:0xf
	v_max_f32_dpp v216, v216, v216 row_bcast:31 row_mask:0xc bank_mask:0xf
	v_max_f32_dpp v217, v217, v217 row_bcast:31 row_mask:0xc bank_mask:0xf
	v_max_f32_dpp v218, v218, v218 row_bcast:31 row_mask:0xc bank_mask:0xf
	v_max_f32_dpp v219, v219, v219 row_bcast:31 row_mask:0xc bank_mask:0xf
	s_nop 0
	v_readlane_b32 s84, v216, 63
	v_readlane_b32 s85, v217, 63
	v_readlane_b32 s86, v218, 63
	v_readlane_b32 s87, v219, 63
	s_nop 1
	v_subrev_f32_e32 v108, s84, v108
	v_subrev_f32_e32 v109, s85, v109
	v_subrev_f32_e32 v110, s86, v110
	v_subrev_f32_e32 v111, s87, v111
	v_subrev_f32_e32 v112, s84, v112
	v_subrev_f32_e32 v113, s85, v113
	v_subrev_f32_e32 v114, s86, v114
	v_subrev_f32_e32 v115, s87, v115
	v_subrev_f32_e32 v116, s84, v116
	v_subrev_f32_e32 v117, s85, v117
	v_subrev_f32_e32 v118, s86, v118
	v_subrev_f32_e32 v119, s87, v119
	v_subrev_f32_e32 v120, s84, v120
	v_subrev_f32_e32 v121, s85, v121
	v_subrev_f32_e32 v122, s86, v122
	v_subrev_f32_e32 v123, s87, v123
	v_mul_f32_e32 v108, 0x3fb8aa3b, v108
	v_mul_f32_e32 v109, 0x3fb8aa3b, v109
	v_mul_f32_e32 v110, 0x3fb8aa3b, v110
	v_mul_f32_e32 v111, 0x3fb8aa3b, v111
	v_mul_f32_e32 v112, 0x3fb8aa3b, v112
	v_mul_f32_e32 v113, 0x3fb8aa3b, v113
	v_mul_f32_e32 v114, 0x3fb8aa3b, v114
	v_mul_f32_e32 v115, 0x3fb8aa3b, v115
	v_mul_f32_e32 v116, 0x3fb8aa3b, v116
	v_mul_f32_e32 v117, 0x3fb8aa3b, v117
	v_mul_f32_e32 v118, 0x3fb8aa3b, v118
	v_mul_f32_e32 v119, 0x3fb8aa3b, v119
	v_mul_f32_e32 v120, 0x3fb8aa3b, v120
	v_mul_f32_e32 v121, 0x3fb8aa3b, v121
	v_mul_f32_e32 v122, 0x3fb8aa3b, v122
	v_mul_f32_e32 v123, 0x3fb8aa3b, v123
	v_exp_f32_e32 v108, v108
	v_exp_f32_e32 v109, v109
	v_exp_f32_e32 v110, v110
	v_exp_f32_e32 v111, v111
	v_exp_f32_e32 v112, v112
	v_exp_f32_e32 v113, v113
	v_exp_f32_e32 v114, v114
	v_exp_f32_e32 v115, v115
	v_exp_f32_e32 v116, v116
	v_exp_f32_e32 v117, v117
	v_exp_f32_e32 v118, v118
	v_exp_f32_e32 v119, v119
	v_exp_f32_e32 v120, v120
	v_exp_f32_e32 v121, v121
	v_exp_f32_e32 v122, v122
	v_exp_f32_e32 v123, v123
	s_cmp_eq_u32 s73, 0x100
	s_cbranch_scc1 .Lau_nomask2
	s_nop 0
	v_cndmask_b32_e64 v108, 0, v108, s[24:25]
	v_cndmask_b32_e64 v109, 0, v109, s[24:25]
	v_cndmask_b32_e64 v110, 0, v110, s[24:25]
	v_cndmask_b32_e64 v111, 0, v111, s[24:25]
	v_cndmask_b32_e64 v112, 0, v112, s[26:27]
	v_cndmask_b32_e64 v113, 0, v113, s[26:27]
	v_cndmask_b32_e64 v114, 0, v114, s[26:27]
	v_cndmask_b32_e64 v115, 0, v115, s[26:27]
	v_cndmask_b32_e64 v116, 0, v116, s[28:29]
	v_cndmask_b32_e64 v117, 0, v117, s[28:29]
	v_cndmask_b32_e64 v118, 0, v118, s[28:29]
	v_cndmask_b32_e64 v119, 0, v119, s[28:29]
	v_cndmask_b32_e64 v120, 0, v120, s[30:31]
	v_cndmask_b32_e64 v121, 0, v121, s[30:31]
	v_cndmask_b32_e64 v122, 0, v122, s[30:31]
	v_cndmask_b32_e64 v123, 0, v123, s[30:31]
.Lau_nomask2:
	s_nop 0
	v_add_f32_e32 v216, 0, v108
	v_add_f32_e32 v217, 0, v109
	v_add_f32_e32 v218, 0, v110
	v_add_f32_e32 v219, 0, v111
	v_add_f32_e32 v216, v112, v216
	v_add_f32_e32 v217, v113, v217
	v_add_f32_e32 v218, v114, v218
	v_add_f32_e32 v219, v115, v219
	v_add_f32_e32 v216, v116, v216
	v_add_f32_e32 v217, v117, v217
	v_add_f32_e32 v218, v118, v218
	v_add_f32_e32 v219, v119, v219
	v_add_f32_e32 v216, v120, v216
	v_add_f32_e32 v217, v121, v217
	v_add_f32_e32 v218, v122, v218
	v_add_f32_e32 v219, v123, v219
	v_add_f32_dpp v216, v216, v216 quad_perm:[1,0,3,2] row_mask:0xf bank_mask:0xf bound_ctrl:1
	v_add_f32_dpp v217, v217, v217 quad_perm:[1,0,3,2] row_mask:0xf bank_mask:0xf bound_ctrl:1
	v_add_f32_dpp v218, v218, v218 quad_perm:[1,0,3,2] row_mask:0xf bank_mask:0xf bound_ctrl:1
	v_add_f32_dpp v219, v219, v219 quad_perm:[1,0,3,2] row_mask:0xf bank_mask:0xf bound_ctrl:1
	v_add_f32_dpp v216, v216, v216 quad_perm:[2,3,0,1] row_mask:0xf bank_mask:0xf bound_ctrl:1
	v_add_f32_dpp v217, v217, v217 quad_perm:[2,3,0,1] row_mask:0xf bank_mask:0xf bound_ctrl:1
	v_add_f32_dpp v218, v218, v218 quad_perm:[2,3,0,1] row_mask:0xf bank_mask:0xf bound_ctrl:1
	v_add_f32_dpp v219, v219, v219 quad_perm:[2,3,0,1] row_mask:0xf bank_mask:0xf bound_ctrl:1
	v_add_f32_dpp v216, v216, v216 row_half_mirror row_mask:0xf bank_mask:0xf bound_ctrl:1
	v_add_f32_dpp v217, v217, v217 row_half_mirror row_mask:0xf bank_mask:0xf bound_ctrl:1
	v_add_f32_dpp v218, v218, v218 row_half_mirror row_mask:0xf bank_mask:0xf bound_ctrl:1
	v_add_f32_dpp v219, v219, v219 row_half_mirror row_mask:0xf bank_mask:0xf bound_ctrl:1
	v_add_f32_dpp v216, v216, v216 row_mirror row_mask:0xf bank_mask:0xf bound_ctrl:1
	v_add_f32_dpp v217, v217, v217 row_mirror row_mask:0xf bank_mask:0xf bound_ctrl:1
	v_add_f32_dpp v218, v218, v218 row_mirror row_mask:0xf bank_mask:0xf bound_ctrl:1
	v_add_f32_dpp v219, v219, v219 row_mirror row_mask:0xf bank_mask:0xf bound_ctrl:1
	v_add_f32_dpp v216, v216, v216 row_bcast:15 row_mask:0xa bank_mask:0xf
	v_add_f32_dpp v217, v217, v217 row_bcast:15 row_mask:0xa bank_mask:0xf
	v_add_f32_dpp v218, v218, v218 row_bcast:15 row_mask:0xa bank_mask:0xf
	v_add_f32_dpp v219, v219, v219 row_bcast:15 row_mask:0xa bank_mask:0xf
	v_add_f32_dpp v216, v216, v216 row_bcast:31 row_mask:0xc bank_mask:0xf
	v_add_f32_dpp v217, v217, v217 row_bcast:31 row_mask:0xc bank_mask:0xf
	v_add_f32_dpp v218, v218, v218 row_bcast:31 row_mask:0xc bank_mask:0xf
	v_add_f32_dpp v219, v219, v219 row_bcast:31 row_mask:0xc bank_mask:0xf
	s_nop 0
	v_readlane_b32 s84, v216, 63
	v_readlane_b32 s85, v217, 63
	v_readlane_b32 s86, v218, 63
	v_readlane_b32 s87, v219, 63
	s_nop 1
	v_mov_b32_e32 v216, s84
	v_mov_b32_e32 v217, s85
	v_mov_b32_e32 v218, s86
	v_mov_b32_e32 v219, s87
	v_div_scale_f32 v220, s[8:9], v216, v216, 1.0
	v_div_scale_f32 v221, s[8:9], v217, v217, 1.0
	v_div_scale_f32 v222, s[8:9], v218, v218, 1.0
	v_div_scale_f32 v223, s[8:9], v219, v219, 1.0
	v_rcp_f32_e32 v128, v220
	v_rcp_f32_e32 v129, v221
	v_rcp_f32_e32 v130, v222
	v_rcp_f32_e32 v131, v223
	s_nop 0
	v_fma_f32 v124, -v220, v128, 1.0
	v_fma_f32 v125, -v221, v129, 1.0
	v_fma_f32 v126, -v222, v130, 1.0
	v_fma_f32 v127, -v223, v131, 1.0
	v_fmac_f32_e32 v128, v124, v128
	v_fmac_f32_e32 v129, v125, v129
	v_fmac_f32_e32 v130, v126, v130
	v_fmac_f32_e32 v131, v127, v131
	v_div_scale_f32 v224, vcc, 1.0, v216, 1.0
	v_mul_f32_e32 v225, v224, v128
	v_fma_f32 v134, -v220, v225, v224
	v_fmac_f32_e32 v225, v134, v128
	v_fma_f32 v220, -v220, v225, v224
	s_nop 0
	v_div_fmas_f32 v220, v220, v128, v225
	v_div_fixup_f32 v220, v220, v216, 1.0
	v_div_scale_f32 v224, vcc, 1.0, v217, 1.0
	v_mul_f32_e32 v225, v224, v129
	v_fma_f32 v134, -v221, v225, v224
	v_fmac_f32_e32 v225, v134, v129
	v_fma_f32 v221, -v221, v225, v224
	s_nop 0
	v_div_fmas_f32 v221, v221, v129, v225
	v_div_fixup_f32 v221, v221, v217, 1.0
	v_div_scale_f32 v224, vcc, 1.0, v218, 1.0
	v_mul_f32_e32 v225, v224, v130
	v_fma_f32 v134, -v222, v225, v224
	v_fmac_f32_e32 v225, v134, v130
	v_fma_f32 v222, -v222, v225, v224
	s_nop 0
	v_div_fmas_f32 v222, v222, v130, v225
	v_div_fixup_f32 v222, v222, v218, 1.0
	v_div_scale_f32 v224, vcc, 1.0, v219, 1.0
	v_mul_f32_e32 v225, v224, v131
	v_fma_f32 v134, -v223, v225, v224
	v_fmac_f32_e32 v225, v134, v131
	v_fma_f32 v223, -v223, v225, v224
	s_nop 0
	v_div_fmas_f32 v223, v223, v131, v225
	v_div_fixup_f32 v223, v223, v219, 1.0
	v_mul_f32_e32 v108, v108, v220
	v_mul_f32_e32 v109, v109, v221
	v_mul_f32_e32 v110, v110, v222
	v_mul_f32_e32 v111, v111, v223
	v_mul_f32_e32 v112, v112, v220
	v_mul_f32_e32 v113, v113, v221
	v_mul_f32_e32 v114, v114, v222
	v_mul_f32_e32 v115, v115, v223
	v_mul_f32_e32 v116, v116, v220
	v_mul_f32_e32 v117, v117, v221
	v_mul_f32_e32 v118, v118, v222
	v_mul_f32_e32 v119, v119, v223
	v_mul_f32_e32 v120, v120, v220
	v_mul_f32_e32 v121, v121, v221
	v_mul_f32_e32 v122, v122, v222
	v_mul_f32_e32 v123, v123, v223
	v_cvt_pk_bf16_f32 v108, v108, v108
	v_cvt_pk_bf16_f32 v109, v109, v109
	v_cvt_pk_bf16_f32 v110, v110, v110
	v_cvt_pk_bf16_f32 v111, v111, v111
	v_cvt_pk_bf16_f32 v112, v112, v112
	v_cvt_pk_bf16_f32 v113, v113, v113
	v_cvt_pk_bf16_f32 v114, v114, v114
	v_cvt_pk_bf16_f32 v115, v115, v115
	v_cvt_pk_bf16_f32 v116, v116, v116
	v_cvt_pk_bf16_f32 v117, v117, v117
	v_cvt_pk_bf16_f32 v118, v118, v118
	v_cvt_pk_bf16_f32 v119, v119, v119
	v_cvt_pk_bf16_f32 v120, v120, v120
	v_cvt_pk_bf16_f32 v121, v121, v121
	v_cvt_pk_bf16_f32 v122, v122, v122
	v_cvt_pk_bf16_f32 v123, v123, v123
	ds_write_b16 v88, v108 offset:0
	ds_write_b16 v88, v109 offset:512
	ds_write_b16 v88, v110 offset:1024
	ds_write_b16 v88, v111 offset:1536
	ds_write_b16 v88, v112 offset:128
	ds_write_b16 v88, v113 offset:640
	ds_write_b16 v88, v114 offset:1152
	ds_write_b16 v88, v115 offset:1664
	ds_write_b16 v88, v116 offset:256
	ds_write_b16 v88, v117 offset:768
	ds_write_b16 v88, v118 offset:1280
	ds_write_b16 v88, v119 offset:1792
	ds_write_b16 v88, v120 offset:384
	ds_write_b16 v88, v121 offset:896
	ds_write_b16 v88, v122 offset:1408
	ds_write_b16 v88, v123 offset:1920
	s_waitcnt vmcnt(8)
	s_waitcnt lgkmcnt(0)
	ds_read_b128 v[172:175], v89 offset:0
	ds_read_b64_tr_b16 v[140:141], v78 offset:9216
	ds_read_b64_tr_b16 v[142:143], v78 offset:10240
	ds_read_b64_tr_b16 v[144:145], v79 offset:9216
	ds_read_b64_tr_b16 v[146:147], v79 offset:10240
	ds_read_b64_tr_b16 v[148:149], v80 offset:9216
	ds_read_b64_tr_b16 v[150:151], v80 offset:10240
	ds_read_b64_tr_b16 v[152:153], v81 offset:9216
	ds_read_b64_tr_b16 v[154:155], v81 offset:10240
	ds_read_b64_tr_b16 v[156:157], v82 offset:9216
	ds_read_b64_tr_b16 v[158:159], v82 offset:10240
	ds_read_b64_tr_b16 v[160:161], v83 offset:9216
	ds_read_b64_tr_b16 v[162:163], v83 offset:10240
	ds_read_b64_tr_b16 v[164:165], v84 offset:9216
	ds_read_b64_tr_b16 v[166:167], v84 offset:10240
	ds_read_b64_tr_b16 v[168:169], v85 offset:9216
	ds_read_b64_tr_b16 v[170:171], v85 offset:10240
	s_waitcnt lgkmcnt(0)
	v_mfma_f32_16x16x32_bf16 v[184:187], v[172:175], v[140:143], 0
	v_mfma_f32_16x16x32_bf16 v[188:191], v[172:175], v[144:147], 0
	v_mfma_f32_16x16x32_bf16 v[192:195], v[172:175], v[148:151], 0
	v_mfma_f32_16x16x32_bf16 v[196:199], v[172:175], v[152:155], 0
	v_mfma_f32_16x16x32_bf16 v[200:203], v[172:175], v[156:159], 0
	v_mfma_f32_16x16x32_bf16 v[204:207], v[172:175], v[160:163], 0
	v_mfma_f32_16x16x32_bf16 v[208:211], v[172:175], v[164:167], 0
	v_mfma_f32_16x16x32_bf16 v[212:215], v[172:175], v[168:171], 0
	s_add_i32 m0, s75, 0x2400
	s_nop 0
	global_load_lds_dwordx4 v26, s[2:3]
	s_add_i32 m0, s75, 0x2800
	s_nop 0
	global_load_lds_dwordx4 v27, s[2:3]
	s_add_i32 m0, s75, 0x2c00
	s_nop 0
	global_load_lds_dwordx4 v28, s[2:3]
	s_add_i32 m0, s75, 0x3000
	s_nop 0
	global_load_lds_dwordx4 v29, s[2:3]
	s_add_i32 m0, s75, 0x3400
	s_nop 0
	global_load_lds_dwordx4 v30, s[2:3]
	s_add_i32 m0, s75, 0x3800
	s_nop 0
	global_load_lds_dwordx4 v31, s[2:3]
	s_add_i32 m0, s75, 0x3c00
	s_nop 0
	global_load_lds_dwordx4 v32, s[2:3]
	s_add_i32 m0, s75, 0x4000
	s_nop 0
	global_load_lds_dwordx4 v33, s[2:3]
	s_waitcnt vmcnt(8)
	ds_read_b128 v[172:175], v89 offset:64
	ds_read_b64_tr_b16 v[140:141], v78 offset:1024
	ds_read_b64_tr_b16 v[142:143], v78 offset:2048
	ds_read_b64_tr_b16 v[144:145], v79 offset:1024
	ds_read_b64_tr_b16 v[146:147], v79 offset:2048
	ds_read_b64_tr_b16 v[148:149], v80 offset:1024
	ds_read_b64_tr_b16 v[150:151], v80 offset:2048
	ds_read_b64_tr_b16 v[152:153], v81 offset:1024
	ds_read_b64_tr_b16 v[154:155], v81 offset:2048
	ds_read_b64_tr_b16 v[156:157], v82 offset:1024
	ds_read_b64_tr_b16 v[158:159], v82 offset:2048
	ds_read_b64_tr_b16 v[160:161], v83 offset:1024
	ds_read_b64_tr_b16 v[162:163], v83 offset:2048
	ds_read_b64_tr_b16 v[164:165], v84 offset:1024
	ds_read_b64_tr_b16 v[166:167], v84 offset:2048
	ds_read_b64_tr_b16 v[168:169], v85 offset:1024
	ds_read_b64_tr_b16 v[170:171], v85 offset:2048
	s_waitcnt lgkmcnt(0)
	v_mfma_f32_16x16x32_bf16 v[184:187], v[172:175], v[140:143], v[184:187]
	v_mfma_f32_16x16x32_bf16 v[188:191], v[172:175], v[144:147], v[188:191]
	v_mfma_f32_16x16x32_bf16 v[192:195], v[172:175], v[148:151], v[192:195]
	v_mfma_f32_16x16x32_bf16 v[196:199], v[172:175], v[152:155], v[196:199]
	v_mfma_f32_16x16x32_bf16 v[200:203], v[172:175], v[156:159], v[200:203]
	v_mfma_f32_16x16x32_bf16 v[204:207], v[172:175], v[160:163], v[204:207]
	v_mfma_f32_16x16x32_bf16 v[208:211], v[172:175], v[164:167], v[208:211]
	v_mfma_f32_16x16x32_bf16 v[212:215], v[172:175], v[168:171], v[212:215]
	s_add_i32 m0, s75, 0x400
	s_nop 0
	global_load_lds_dwordx4 v34, s[2:3]
	s_add_i32 m0, s75, 0x800
	s_nop 0
	global_load_lds_dwordx4 v35, s[2:3]
	s_add_i32 m0, s75, 0xc00
	s_nop 0
	global_load_lds_dwordx4 v36, s[2:3]
	s_add_i32 m0, s75, 0x1000
	s_nop 0
	global_load_lds_dwordx4 v37, s[2:3]
	s_add_i32 m0, s75, 0x1400
	s_nop 0
	global_load_lds_dwordx4 v38, s[2:3]
	s_add_i32 m0, s75, 0x1800
	s_nop 0
	global_load_lds_dwordx4 v39, s[2:3]
	s_add_i32 m0, s75, 0x1c00
	s_nop 0
	global_load_lds_dwordx4 v40, s[2:3]
	s_add_i32 m0, s75, 0x2000
	s_nop 0
	global_load_lds_dwordx4 v41, s[2:3]
	s_waitcnt vmcnt(8)
	ds_read_b128 v[172:175], v89 offset:128
	ds_read_b64_tr_b16 v[140:141], v78 offset:9216
	ds_read_b64_tr_b16 v[142:143], v78 offset:10240
	ds_read_b64_tr_b16 v[144:145], v79 offset:9216
	ds_read_b64_tr_b16 v[146:147], v79 offset:10240
	ds_read_b64_tr_b16 v[148:149], v80 offset:9216
	ds_read_b64_tr_b16 v[150:151], v80 offset:10240
	ds_read_b64_tr_b16 v[152:153], v81 offset:9216
	ds_read_b64_tr_b16 v[154:155], v81 offset:10240
	ds_read_b64_tr_b16 v[156:157], v82 offset:9216
	ds_read_b64_tr_b16 v[158:159], v82 offset:10240
	ds_read_b64_tr_b16 v[160:161], v83 offset:9216
	ds_read_b64_tr_b16 v[162:163], v83 offset:10240
	ds_read_b64_tr_b16 v[164:165], v84 offset:9216
	ds_read_b64_tr_b16 v[166:167], v84 offset:10240
	ds_read_b64_tr_b16 v[168:169], v85 offset:9216
	ds_read_b64_tr_b16 v[170:171], v85 offset:10240
	s_waitcnt lgkmcnt(0)
	v_mfma_f32_16x16x32_bf16 v[184:187], v[172:175], v[140:143], v[184:187]
	v_mfma_f32_16x16x32_bf16 v[188:191], v[172:175], v[144:147], v[188:191]
	v_mfma_f32_16x16x32_bf16 v[192:195], v[172:175], v[148:151], v[192:195]
	v_mfma_f32_16x16x32_bf16 v[196:199], v[172:175], v[152:155], v[196:199]
	v_mfma_f32_16x16x32_bf16 v[200:203], v[172:175], v[156:159], v[200:203]
	v_mfma_f32_16x16x32_bf16 v[204:207], v[172:175], v[160:163], v[204:207]
	v_mfma_f32_16x16x32_bf16 v[208:211], v[172:175], v[164:167], v[208:211]
	v_mfma_f32_16x16x32_bf16 v[212:215], v[172:175], v[168:171], v[212:215]
	s_add_i32 m0, s75, 0x2400
	s_nop 0
	global_load_lds_dwordx4 v42, s[2:3]
	s_add_i32 m0, s75, 0x2800
	s_nop 0
	global_load_lds_dwordx4 v43, s[2:3]
	s_add_i32 m0, s75, 0x2c00
	s_nop 0
	global_load_lds_dwordx4 v44, s[2:3]
	s_add_i32 m0, s75, 0x3000
	s_nop 0
	global_load_lds_dwordx4 v45, s[2:3]
	s_add_i32 m0, s75, 0x3400
	s_nop 0
	global_load_lds_dwordx4 v46, s[2:3]
	s_add_i32 m0, s75, 0x3800
	s_nop 0
	global_load_lds_dwordx4 v47, s[2:3]
	s_add_i32 m0, s75, 0x3c00
	s_nop 0
	global_load_lds_dwordx4 v48, s[2:3]
	s_add_i32 m0, s75, 0x4000
	s_nop 0
	global_load_lds_dwordx4 v49, s[2:3]
	s_waitcnt vmcnt(8)
	ds_read_b128 v[172:175], v89 offset:192
	ds_read_b64_tr_b16 v[140:141], v78 offset:1024
	ds_read_b64_tr_b16 v[142:143], v78 offset:2048
	ds_read_b64_tr_b16 v[144:145], v79 offset:1024
	ds_read_b64_tr_b16 v[146:147], v79 offset:2048
	ds_read_b64_tr_b16 v[148:149], v80 offset:1024
	ds_read_b64_tr_b16 v[150:151], v80 offset:2048
	ds_read_b64_tr_b16 v[152:153], v81 offset:1024
	ds_read_b64_tr_b16 v[154:155], v81 offset:2048
	ds_read_b64_tr_b16 v[156:157], v82 offset:1024
	ds_read_b64_tr_b16 v[158:159], v82 offset:2048
	ds_read_b64_tr_b16 v[160:161], v83 offset:1024
	ds_read_b64_tr_b16 v[162:163], v83 offset:2048
	ds_read_b64_tr_b16 v[164:165], v84 offset:1024
	ds_read_b64_tr_b16 v[166:167], v84 offset:2048
	ds_read_b64_tr_b16 v[168:169], v85 offset:1024
	ds_read_b64_tr_b16 v[170:171], v85 offset:2048
	s_waitcnt lgkmcnt(0)
	v_mfma_f32_16x16x32_bf16 v[184:187], v[172:175], v[140:143], v[184:187]
	v_mfma_f32_16x16x32_bf16 v[188:191], v[172:175], v[144:147], v[188:191]
	v_mfma_f32_16x16x32_bf16 v[192:195], v[172:175], v[148:151], v[192:195]
	v_mfma_f32_16x16x32_bf16 v[196:199], v[172:175], v[152:155], v[196:199]
	v_mfma_f32_16x16x32_bf16 v[200:203], v[172:175], v[156:159], v[200:203]
	v_mfma_f32_16x16x32_bf16 v[204:207], v[172:175], v[160:163], v[204:207]
	v_mfma_f32_16x16x32_bf16 v[208:211], v[172:175], v[164:167], v[208:211]
	v_mfma_f32_16x16x32_bf16 v[212:215], v[172:175], v[168:171], v[212:215]
	s_add_i32 m0, s75, 0x400
	s_nop 0
	global_load_lds_dwordx4 v50, s[2:3]
	s_add_i32 m0, s75, 0x800
	s_nop 0
	global_load_lds_dwordx4 v51, s[2:3]
	s_add_i32 m0, s75, 0xc00
	s_nop 0
	global_load_lds_dwordx4 v52, s[2:3]
	s_add_i32 m0, s75, 0x1000
	s_nop 0
	global_load_lds_dwordx4 v53, s[2:3]
	s_add_i32 m0, s75, 0x1400
	s_nop 0
	global_load_lds_dwordx4 v54, s[2:3]
	s_add_i32 m0, s75, 0x1800
	s_nop 0
	global_load_lds_dwordx4 v55, s[2:3]
	s_add_i32 m0, s75, 0x1c00
	s_nop 0
	global_load_lds_dwordx4 v56, s[2:3]
	s_add_i32 m0, s75, 0x2000
	s_nop 0
	global_load_lds_dwordx4 v57, s[2:3]
	s_waitcnt vmcnt(8)
	ds_read_b128 v[172:175], v89 offset:256
	ds_read_b64_tr_b16 v[140:141], v78 offset:9216
	ds_read_b64_tr_b16 v[142:143], v78 offset:10240
	ds_read_b64_tr_b16 v[144:145], v79 offset:9216
	ds_read_b64_tr_b16 v[146:147], v79 offset:10240
	ds_read_b64_tr_b16 v[148:149], v80 offset:9216
	ds_read_b64_tr_b16 v[150:151], v80 offset:10240
	ds_read_b64_tr_b16 v[152:153], v81 offset:9216
	ds_read_b64_tr_b16 v[154:155], v81 offset:10240
	ds_read_b64_tr_b16 v[156:157], v82 offset:9216
	ds_read_b64_tr_b16 v[158:159], v82 offset:10240
	ds_read_b64_tr_b16 v[160:161], v83 offset:9216
	ds_read_b64_tr_b16 v[162:163], v83 offset:10240
	ds_read_b64_tr_b16 v[164:165], v84 offset:9216
	ds_read_b64_tr_b16 v[166:167], v84 offset:10240
	ds_read_b64_tr_b16 v[168:169], v85 offset:9216
	ds_read_b64_tr_b16 v[170:171], v85 offset:10240
	s_waitcnt lgkmcnt(0)
	v_mfma_f32_16x16x32_bf16 v[184:187], v[172:175], v[140:143], v[184:187]
	v_mfma_f32_16x16x32_bf16 v[188:191], v[172:175], v[144:147], v[188:191]
	v_mfma_f32_16x16x32_bf16 v[192:195], v[172:175], v[148:151], v[192:195]
	v_mfma_f32_16x16x32_bf16 v[196:199], v[172:175], v[152:155], v[196:199]
	v_mfma_f32_16x16x32_bf16 v[200:203], v[172:175], v[156:159], v[200:203]
	v_mfma_f32_16x16x32_bf16 v[204:207], v[172:175], v[160:163], v[204:207]
	v_mfma_f32_16x16x32_bf16 v[208:211], v[172:175], v[164:167], v[208:211]
	v_mfma_f32_16x16x32_bf16 v[212:215], v[172:175], v[168:171], v[212:215]
	s_add_i32 m0, s75, 0x2400
	s_nop 0
	global_load_lds_dwordx4 v58, s[2:3]
	s_add_i32 m0, s75, 0x2800
	s_nop 0
	global_load_lds_dwordx4 v59, s[2:3]
	s_add_i32 m0, s75, 0x2c00
	s_nop 0
	global_load_lds_dwordx4 v60, s[2:3]
	s_add_i32 m0, s75, 0x3000
	s_nop 0
	global_load_lds_dwordx4 v61, s[2:3]
	s_add_i32 m0, s75, 0x3400
	s_nop 0
	global_load_lds_dwordx4 v62, s[2:3]
	s_add_i32 m0, s75, 0x3800
	s_nop 0
	global_load_lds_dwordx4 v63, s[2:3]
	s_add_i32 m0, s75, 0x3c00
	s_nop 0
	global_load_lds_dwordx4 v64, s[2:3]
	s_add_i32 m0, s75, 0x4000
	s_nop 0
	global_load_lds_dwordx4 v65, s[2:3]
	s_waitcnt vmcnt(8)
	ds_read_b128 v[172:175], v89 offset:320
	ds_read_b64_tr_b16 v[140:141], v78 offset:1024
	ds_read_b64_tr_b16 v[142:143], v78 offset:2048
	ds_read_b64_tr_b16 v[144:145], v79 offset:1024
	ds_read_b64_tr_b16 v[146:147], v79 offset:2048
	ds_read_b64_tr_b16 v[148:149], v80 offset:1024
	ds_read_b64_tr_b16 v[150:151], v80 offset:2048
	ds_read_b64_tr_b16 v[152:153], v81 offset:1024
	ds_read_b64_tr_b16 v[154:155], v81 offset:2048
	ds_read_b64_tr_b16 v[156:157], v82 offset:1024
	ds_read_b64_tr_b16 v[158:159], v82 offset:2048
	ds_read_b64_tr_b16 v[160:161], v83 offset:1024
	ds_read_b64_tr_b16 v[162:163], v83 offset:2048
	ds_read_b64_tr_b16 v[164:165], v84 offset:1024
	ds_read_b64_tr_b16 v[166:167], v84 offset:2048
	ds_read_b64_tr_b16 v[168:169], v85 offset:1024
	ds_read_b64_tr_b16 v[170:171], v85 offset:2048
	s_waitcnt lgkmcnt(0)
	v_mfma_f32_16x16x32_bf16 v[184:187], v[172:175], v[140:143], v[184:187]
	v_mfma_f32_16x16x32_bf16 v[188:191], v[172:175], v[144:147], v[188:191]
	v_mfma_f32_16x16x32_bf16 v[192:195], v[172:175], v[148:151], v[192:195]
	v_mfma_f32_16x16x32_bf16 v[196:199], v[172:175], v[152:155], v[196:199]
	v_mfma_f32_16x16x32_bf16 v[200:203], v[172:175], v[156:159], v[200:203]
	v_mfma_f32_16x16x32_bf16 v[204:207], v[172:175], v[160:163], v[204:207]
	v_mfma_f32_16x16x32_bf16 v[208:211], v[172:175], v[164:167], v[208:211]
	v_mfma_f32_16x16x32_bf16 v[212:215], v[172:175], v[168:171], v[212:215]
	s_add_i32 m0, s75, 0x400
	s_nop 0
	global_load_lds_dwordx4 v66, s[2:3]
	s_add_i32 m0, s75, 0x800
	s_nop 0
	global_load_lds_dwordx4 v67, s[2:3]
	s_add_i32 m0, s75, 0xc00
	s_nop 0
	global_load_lds_dwordx4 v68, s[2:3]
	s_add_i32 m0, s75, 0x1000
	s_nop 0
	global_load_lds_dwordx4 v69, s[2:3]
	s_add_i32 m0, s75, 0x1400
	s_nop 0
	global_load_lds_dwordx4 v70, s[2:3]
	s_add_i32 m0, s75, 0x1800
	s_nop 0
	global_load_lds_dwordx4 v71, s[2:3]
	s_add_i32 m0, s75, 0x1c00
	s_nop 0
	global_load_lds_dwordx4 v72, s[2:3]
	s_add_i32 m0, s75, 0x2000
	s_nop 0
	global_load_lds_dwordx4 v73, s[2:3]
	s_waitcnt vmcnt(8)
	ds_read_b128 v[172:175], v89 offset:384
	ds_read_b64_tr_b16 v[140:141], v78 offset:9216
	ds_read_b64_tr_b16 v[142:143], v78 offset:10240
	ds_read_b64_tr_b16 v[144:145], v79 offset:9216
	ds_read_b64_tr_b16 v[146:147], v79 offset:10240
	ds_read_b64_tr_b16 v[148:149], v80 offset:9216
	ds_read_b64_tr_b16 v[150:151], v80 offset:10240
	ds_read_b64_tr_b16 v[152:153], v81 offset:9216
	ds_read_b64_tr_b16 v[154:155], v81 offset:10240
	ds_read_b64_tr_b16 v[156:157], v82 offset:9216
	ds_read_b64_tr_b16 v[158:159], v82 offset:10240
	ds_read_b64_tr_b16 v[160:161], v83 offset:9216
	ds_read_b64_tr_b16 v[162:163], v83 offset:10240
	ds_read_b64_tr_b16 v[164:165], v84 offset:9216
	ds_read_b64_tr_b16 v[166:167], v84 offset:10240
	ds_read_b64_tr_b16 v[168:169], v85 offset:9216
	ds_read_b64_tr_b16 v[170:171], v85 offset:10240
	s_waitcnt lgkmcnt(0)
	v_mfma_f32_16x16x32_bf16 v[184:187], v[172:175], v[140:143], v[184:187]
	v_mfma_f32_16x16x32_bf16 v[188:191], v[172:175], v[144:147], v[188:191]
	v_mfma_f32_16x16x32_bf16 v[192:195], v[172:175], v[148:151], v[192:195]
	v_mfma_f32_16x16x32_bf16 v[196:199], v[172:175], v[152:155], v[196:199]
	v_mfma_f32_16x16x32_bf16 v[200:203], v[172:175], v[156:159], v[200:203]
	v_mfma_f32_16x16x32_bf16 v[204:207], v[172:175], v[160:163], v[204:207]
	v_mfma_f32_16x16x32_bf16 v[208:211], v[172:175], v[164:167], v[208:211]
	v_mfma_f32_16x16x32_bf16 v[212:215], v[172:175], v[168:171], v[212:215]
	s_waitcnt vmcnt(0)
	ds_read_b128 v[172:175], v89 offset:448
	ds_read_b64_tr_b16 v[140:141], v78 offset:1024
	ds_read_b64_tr_b16 v[142:143], v78 offset:2048
	ds_read_b64_tr_b16 v[144:145], v79 offset:1024
	ds_read_b64_tr_b16 v[146:147], v79 offset:2048
	ds_read_b64_tr_b16 v[148:149], v80 offset:1024
	ds_read_b64_tr_b16 v[150:151], v80 offset:2048
	ds_read_b64_tr_b16 v[152:153], v81 offset:1024
	ds_read_b64_tr_b16 v[154:155], v81 offset:2048
	ds_read_b64_tr_b16 v[156:157], v82 offset:1024
	ds_read_b64_tr_b16 v[158:159], v82 offset:2048
	ds_read_b64_tr_b16 v[160:161], v83 offset:1024
	ds_read_b64_tr_b16 v[162:163], v83 offset:2048
	ds_read_b64_tr_b16 v[164:165], v84 offset:1024
	ds_read_b64_tr_b16 v[166:167], v84 offset:2048
	ds_read_b64_tr_b16 v[168:169], v85 offset:1024
	ds_read_b64_tr_b16 v[170:171], v85 offset:2048
	s_waitcnt lgkmcnt(0)
	v_mfma_f32_16x16x32_bf16 v[184:187], v[172:175], v[140:143], v[184:187]
	v_mfma_f32_16x16x32_bf16 v[188:191], v[172:175], v[144:147], v[188:191]
	v_mfma_f32_16x16x32_bf16 v[192:195], v[172:175], v[148:151], v[192:195]
	v_mfma_f32_16x16x32_bf16 v[196:199], v[172:175], v[152:155], v[196:199]
	v_mfma_f32_16x16x32_bf16 v[200:203], v[172:175], v[156:159], v[200:203]
	v_mfma_f32_16x16x32_bf16 v[204:207], v[172:175], v[160:163], v[204:207]
	v_mfma_f32_16x16x32_bf16 v[208:211], v[172:175], v[164:167], v[208:211]
	v_mfma_f32_16x16x32_bf16 v[212:215], v[172:175], v[168:171], v[212:215]
	s_nop 7
	s_mov_b64 exec, 0xffff
	v_cvt_pk_bf16_f32 v140, v184, v184
	v_cvt_pk_bf16_f32 v141, v185, v185
	v_cvt_pk_bf16_f32 v142, v186, v186
	v_cvt_pk_bf16_f32 v143, v187, v187
	v_cvt_pk_bf16_f32 v144, v188, v188
	v_cvt_pk_bf16_f32 v145, v189, v189
	v_cvt_pk_bf16_f32 v146, v190, v190
	v_cvt_pk_bf16_f32 v147, v191, v191
	v_cvt_pk_bf16_f32 v148, v192, v192
	v_cvt_pk_bf16_f32 v149, v193, v193
	v_cvt_pk_bf16_f32 v150, v194, v194
	v_cvt_pk_bf16_f32 v151, v195, v195
	v_cvt_pk_bf16_f32 v152, v196, v196
	v_cvt_pk_bf16_f32 v153, v197, v197
	v_cvt_pk_bf16_f32 v154, v198, v198
	v_cvt_pk_bf16_f32 v155, v199, v199
	v_cvt_pk_bf16_f32 v156, v200, v200
	v_cvt_pk_bf16_f32 v157, v201, v201
	v_cvt_pk_bf16_f32 v158, v202, v202
	v_cvt_pk_bf16_f32 v159, v203, v203
	v_cvt_pk_bf16_f32 v160, v204, v204
	v_cvt_pk_bf16_f32 v161, v205, v205
	v_cvt_pk_bf16_f32 v162, v206, v206
	v_cvt_pk_bf16_f32 v163, v207, v207
	v_cvt_pk_bf16_f32 v164, v208, v208
	v_cvt_pk_bf16_f32 v165, v209, v209
	v_cvt_pk_bf16_f32 v166, v210, v210
	v_cvt_pk_bf16_f32 v167, v211, v211
	v_cvt_pk_bf16_f32 v168, v212, v212
	v_cvt_pk_bf16_f32 v169, v213, v213
	v_cvt_pk_bf16_f32 v170, v214, v214
	v_cvt_pk_bf16_f32 v171, v215, v215
	global_store_short v90, v140, s[6:7] offset:0
	global_store_short v90, v141, s[6:7] offset:256
	global_store_short v90, v142, s[6:7] offset:512
	global_store_short v90, v143, s[6:7] offset:768
	global_store_short v90, v144, s[6:7] offset:32
	global_store_short v90, v145, s[6:7] offset:288
	global_store_short v90, v146, s[6:7] offset:544
	global_store_short v90, v147, s[6:7] offset:800
	global_store_short v90, v148, s[6:7] offset:64
	global_store_short v90, v149, s[6:7] offset:320
	global_store_short v90, v150, s[6:7] offset:576
	global_store_short v90, v151, s[6:7] offset:832
	global_store_short v90, v152, s[6:7] offset:96
	global_store_short v90, v153, s[6:7] offset:352
	global_store_short v90, v154, s[6:7] offset:608
	global_store_short v90, v155, s[6:7] offset:864
	global_store_short v90, v156, s[6:7] offset:128
	global_store_short v90, v157, s[6:7] offset:384
	global_store_short v90, v158, s[6:7] offset:640
	global_store_short v90, v159, s[6:7] offset:896
	global_store_short v90, v160, s[6:7] offset:160
	global_store_short v90, v161, s[6:7] offset:416
	global_store_short v90, v162, s[6:7] offset:672
	global_store_short v90, v163, s[6:7] offset:928
	global_store_short v90, v164, s[6:7] offset:192
	global_store_short v90, v165, s[6:7] offset:448
	global_store_short v90, v166, s[6:7] offset:704
	global_store_short v90, v167, s[6:7] offset:960
	global_store_short v90, v168, s[6:7] offset:224
	global_store_short v90, v169, s[6:7] offset:480
	global_store_short v90, v170, s[6:7] offset:736
	global_store_short v90, v171, s[6:7] offset:992
	s_mov_b64 exec, -1
	s_add_i32 s71, s71, 1
	s_cmp_lt_u32 s71, 2
	s_cbranch_scc1 .Lau_g
	s_cmp_eq_u32 s74, 0
	s_cbranch_scc0 .Lau_ret1
	v_and_b32_e32 v141, 64, v182
	v_add_u32_e32 v4, 64, v141
	v_xor_b32_e32 v5, 32, v182
	v_cmp_lt_i32_e32 vcc, v5, v4
	s_nop 1
	v_cndmask_b32_e32 v5, v182, v5, vcc
	v_lshlrev_b32_e32 v132, 2, v5
	v_xor_b32_e32 v5, 16, v182
	v_cmp_lt_i32_e32 vcc, v5, v4
	s_nop 1
	v_cndmask_b32_e32 v5, v182, v5, vcc
	v_lshlrev_b32_e32 v133, 2, v5
	v_xor_b32_e32 v5, 8, v182
	v_cmp_lt_i32_e32 vcc, v5, v4
	s_nop 1
	v_cndmask_b32_e32 v5, v182, v5, vcc
	v_lshlrev_b32_e32 v136, 2, v5
	v_xor_b32_e32 v5, 4, v182
	v_cmp_lt_i32_e32 vcc, v5, v4
	s_nop 1
	v_cndmask_b32_e32 v5, v182, v5, vcc
	v_lshlrev_b32_e32 v137, 2, v5
	v_xor_b32_e32 v5, 2, v182
	v_cmp_lt_i32_e32 vcc, v5, v4
	s_nop 1
	v_cndmask_b32_e32 v5, v182, v5, vcc
	v_lshlrev_b32_e32 v139, 2, v5
	v_xor_b32_e32 v5, 1, v182
	v_cmp_lt_i32_e32 vcc, v5, v4
	s_nop 1
	v_cndmask_b32_e32 v5, v182, v5, vcc
	v_lshlrev_b32_e32 v140, 2, v5
	s_branch .Lau_ret0
.Lau_ret0:
.LBB0_2653:
	s_xor_b32 s38, s49, 0xfff
	s_or_b32 s0, s48, s38
	v_mov_b32_e32 v1, v0
	v_writelane_b32 v252, s0, 26
	s_lshl_b32 s0, s0, 14
	s_add_u32 s16, s66, s0
	s_waitcnt vmcnt(4)
	v_and_b32_e32 v39, 63, v1
	s_addc_u32 s17, s67, 0
	v_lshlrev_b32_e32 v134, 2, v39
	v_lshl_add_u64 v[2:3], s[16:17], 0, v[134:135]
	s_movk_i32 s0, 0x1000
	v_add_co_u32_e32 v14, vcc, s0, v2
	global_load_dword v37, v134, s[16:17] nt
	global_load_dword v38, v134, s[16:17] offset:256 nt
	global_load_dword v24, v134, s[16:17] offset:512 nt
	global_load_dword v27, v134, s[16:17] offset:768 nt
	global_load_dword v28, v134, s[16:17] offset:1024 nt
	global_load_dword v29, v134, s[16:17] offset:1280 nt
	global_load_dword v30, v134, s[16:17] offset:1536 nt
	global_load_dword v31, v134, s[16:17] offset:1792 nt
	global_load_dword v32, v134, s[16:17] offset:2048 nt
	global_load_dword v23, v134, s[16:17] offset:2304 nt
	global_load_dword v25, v134, s[16:17] offset:2560 nt
	global_load_dword v26, v134, s[16:17] offset:2816 nt
	global_load_dword v21, v134, s[16:17] offset:3072 nt
	global_load_dword v22, v134, s[16:17] offset:3328 nt
	global_load_dword v19, v134, s[16:17] offset:3584 nt
	global_load_dword v20, v134, s[16:17] offset:3840 nt
	v_addc_co_u32_e32 v15, vcc, 0, v3, vcc
	global_load_dword v16, v[14:15], off nt
	global_load_dword v1, v[14:15], off offset:256 nt
	global_load_dword v2, v[14:15], off offset:512 nt
	global_load_dword v3, v[14:15], off offset:768 nt
	global_load_dword v4, v[14:15], off offset:1024 nt
	global_load_dword v5, v[14:15], off offset:1280 nt
	global_load_dword v6, v[14:15], off offset:1536 nt
	global_load_dword v7, v[14:15], off offset:1792 nt
	global_load_dword v18, v[14:15], off offset:2048 nt
	global_load_dword v8, v[14:15], off offset:2304 nt
	global_load_dword v9, v[14:15], off offset:2560 nt
	global_load_dword v10, v[14:15], off offset:2816 nt
	global_load_dword v11, v[14:15], off offset:3072 nt
	global_load_dword v12, v[14:15], off offset:3328 nt
	global_load_dword v13, v[14:15], off offset:3584 nt
	s_nop 0
	global_load_dword v14, v[14:15], off offset:3840 nt
	v_or_b32_e32 v40, 0x800, v39
	v_cmp_lt_u32_e32 vcc, s38, v40
	v_cmp_ge_u32_e64 s[0:1], s38, v40
	s_waitcnt vmcnt(34)
	v_mov_b32_e32 v34, 0
	v_mov_b32_e32 v15, 0
	s_and_saveexec_b64 s[2:3], s[0:1]
	s_cbranch_execz .LBB0_2655
	v_lshlrev_b32_e32 v15, 2, v40
	global_load_dword v15, v15, s[16:17] nt
	s_waitcnt vmcnt(0)
	v_not_b32_e32 v17, v15
	v_or_b32_e32 v33, 0x80000000, v15
	v_cmp_gt_i32_e64 s[0:1], 0, v15
	s_nop 1
	v_cndmask_b32_e64 v15, v33, v17, s[0:1]

.LBB0_2994:
	v_readlane_b32 s8, v251, 19
	v_readlane_b32 s0, v252, 26
	v_readlane_b32 s9, v251, 20
	v_readlane_b32 s10, v251, 21
	v_readlane_b32 s11, v251, 22
	v_readlane_b32 s12, v251, 23
	v_readlane_b32 s13, v251, 24
	v_readlane_b32 s14, v251, 25
	v_readlane_b32 s15, v251, 26
	v_readlane_b32 s16, v251, 27
	v_readlane_b32 s17, v251, 28
	s_lshl_b32 s6, s0, 10
	s_lshl_b32 s0, s0, 11
	v_readlane_b32 s18, v251, 29
	v_readlane_b32 s19, v251, 30
	v_readlane_b32 s20, v251, 31
	v_readlane_b32 s21, v251, 32
	v_readlane_b32 s22, v251, 33
	v_readlane_b32 s23, v251, 34
	s_mov_b64 s[8:9], s[16:17]
	s_add_u32 s0, s8, s0
	s_addc_u32 s1, s9, 0
	s_mov_b32 s7, 0
	s_mov_b64 s[2:3], -1
	s_mov_b64 s[10:11], s[18:19]
	s_mov_b64 s[12:13], s[20:21]
	s_mov_b64 s[14:15], s[22:23]
	v_readlane_b32 s70, v252, 26
	s_mov_b32 s72, s48
	s_movk_i32 s73, 0x100
	s_mov_b32 s74, 1
	s_branch .Lau_entry
.Lau_ret1:
	s_branch .LBB0_2341

	.amdhsa_kernel _ZN2mk4megaENS_6ParamsE
		.amdhsa_group_segment_fixed_size 16384
		.amdhsa_private_segment_fixed_size 0
		.amdhsa_kernarg_size 920
		.amdhsa_user_sgpr_count 2
		.amdhsa_user_sgpr_dispatch_ptr 0
		.amdhsa_user_sgpr_queue_ptr 0
		.amdhsa_user_sgpr_kernarg_segment_ptr 1
		.amdhsa_user_sgpr_dispatch_id 0
		.amdhsa_user_sgpr_kernarg_preload_length 0
		.amdhsa_user_sgpr_kernarg_preload_offset 0
		.amdhsa_user_sgpr_private_segment_size 0
		.amdhsa_uses_dynamic_stack 0
		.amdhsa_enable_private_segment 0
		.amdhsa_system_sgpr_workgroup_id_x 1
		.amdhsa_system_sgpr_workgroup_id_y 0
		.amdhsa_system_sgpr_workgroup_id_z 0
		.amdhsa_system_sgpr_workgroup_info 0
		.amdhsa_system_vgpr_workitem_id 0
		.amdhsa_next_free_vgpr 256
		.amdhsa_next_free_sgpr 102
		.amdhsa_accum_offset 256
		.amdhsa_reserve_vcc 1
		.amdhsa_float_round_mode_32 0
		.amdhsa_float_round_mode_16_64 0
		.amdhsa_float_denorm_mode_32 3
		.amdhsa_float_denorm_mode_16_64 3
		.amdhsa_dx10_clamp 1
		.amdhsa_ieee_mode 1
		.amdhsa_fp16_overflow 0
		.amdhsa_tg_split 0
		.amdhsa_exception_fp_ieee_invalid_op 0
		.amdhsa_exception_fp_denorm_src 0
		.amdhsa_exception_fp_ieee_div_zero 0
		.amdhsa_exception_fp_ieee_overflow 0
		.amdhsa_exception_fp_ieee_underflow 0
		.amdhsa_exception_fp_ieee_inexact 0
		.amdhsa_exception_int_div_zero 0
	.end_amdhsa_kernel

amdhsa.kernels:
  - .agpr_count:     0
    .args:
      - .offset:         0
        .size:           664
        .value_kind:     by_value
      - .offset:         664
        .size:           4
        .value_kind:     hidden_block_count_x
      - .offset:         668
        .size:           4
        .value_kind:     hidden_block_count_y
      - .offset:         672
        .size:           4
        .value_kind:     hidden_block_count_z
      - .offset:         676
        .size:           2
        .value_kind:     hidden_group_size_x
      - .offset:         678
        .size:           2
        .value_kind:     hidden_group_size_y
      - .offset:         680
        .size:           2
        .value_kind:     hidden_group_size_z
      - .offset:         682
        .size:           2
        .value_kind:     hidden_remainder_x
      - .offset:         684
        .size:           2
        .value_kind:     hidden_remainder_y
      - .offset:         686
        .size:           2
        .value_kind:     hidden_remainder_z
      - .offset:         704
        .size:           8
        .value_kind:     hidden_global_offset_x
      - .offset:         712
        .size:           8
        .value_kind:     hidden_global_offset_y
      - .offset:         720
        .size:           8
        .value_kind:     hidden_global_offset_z
      - .offset:         728
        .size:           2
        .value_kind:     hidden_grid_dims
      - .offset:         784
        .size:           4
        .value_kind:     hidden_dynamic_lds_size
    .group_segment_fixed_size: 16384
    .kernarg_segment_align: 8
    .kernarg_segment_size: 920
    .language:       OpenCL C
    .language_version:
      - 2
      - 0
    .max_flat_workgroup_size: 512
    .name:           _ZN2mk4megaENS_6ParamsE
    .private_segment_fixed_size: 0
    .sgpr_count:     108
    .sgpr_spill_count: 277
    .symbol:         _ZN2mk4megaENS_6ParamsE.kd
    .uniform_work_group_size: 1
    .uses_dynamic_stack: false
    .vgpr_count:     256
    .vgpr_spill_count: 0
    .wavefront_size: 64
